# stage-0 body: sign flips folded into neg modifiers of the packed FMAs (20 fewer VALU per pass)
# speedup vs baseline: 1.0047x; 1.0007x over previous
; #define LAS __attribute__((address_space(3)))
; __device__ __forceinline__ unsigned pk2(float lo, float hi) { const f32x2 v = {lo, hi}; return __builtin_bit_cast(unsigned, __builtin_convertvector(v, bf16x2_t)); }
; __device__ __forceinline__ unsigned f2bf(float f) { return pk2(f, 0.f) & 0xffffu; }
; __device__ __forceinline__ float frcp(float x) { return __builtin_amdgcn_rcpf(x); }
; __device__ __forceinline__ float sigmoidf_(float x) { return frcp(1.0f + __expf(-x)); }
; __device__ __forceinline__ void rwkv_chain(LAS unsigned char* lds, int cid, const bf16_t* P0, const float* mu, const float* w0, const float* w2, const float* a0, const float* a2, ...
;     ...
;         { const int tok = tid >> 4, c4 = (tid & 15) * 4;
; #pragma unroll
;         for (int i = 0; i < 5; ++i) {
;             const f32x4 mu4 = *(const LAS f32x4*)(cst + (5 + i) * 64 + c4);
;             const f32x4 cv = (f32x4){bflo(rc[i].x), bfhi(rc[i].x), bflo(rc[i].y), bfhi(rc[i].y)};
;             const f32x4 pv = (f32x4){bflo(rpv[i].x), bfhi(rpv[i].x), bflo(rpv[i].y), bfhi(rpv[i].y)}, nv = (f32x4){bflo(rnx[i].x), bfhi(rnx[i].x), bflo(rnx[i].y), bfhi(rnx[i].y)};
;             const f32x4 xv = cv + mu4 * ((pv + nv) * 0.5f - cv);
;             if (i == 0) *(LAS f32x4*)(rS + tok * 64 + c4) = xv;
;             else if (i == 1) *(LAS f32x4*)(kS + tok * 64 + c4) = xv;
;             else if (i == 2) *(LAS f32x4*)(vS + tok * 64 + c4) = xv;
;             else if (i == 3) { float th[4];
; #pragma unroll
;                 for (int e = 0; e < 4; ++e) { const float ex = __expf(2.f * xv[e]); th[e] = 1.f - 2.f * frcp(ex + 1.f); }
;                 u32x2 w; w.x = pk2(th[0], th[1]); w.y = pk2(th[2], th[3]); *(LAS u32x2*)(wdB + tok * 72 + c4) = w; }
;             else { u32x2 w; w.x = pk2(xv[0], xv[1]); w.y = pk2(xv[2], xv[3]); *(LAS u32x2*)(adB + tok * 72 + c4) = w; }
;         } }
;         if (dir == 0) {
;             const int tok = tid >> 4, c = tid & 15, t = t0 + tok;
;             const float cur = bf2f(gcv), prv = bf2f(gpv), nxt = bf2f(gnv);
;             const float x = cur + cst[10 * 64 + c] * (0.5f * (prv + nxt) - cur);
;             SG[((size_t)b * SEQ + t) * 128 + h * 16 + c] = (bf16_t)f2bf(sigmoidf_(x));
.Lrw_s0_body:
	v_lshlrev_b32_e32 v16, 16, v57
	v_ashrrev_i32_e32 v9, 4, v8
	v_and_b32_e32 v8, 15, v8
	v_lshl_add_u32 v25, v8, 4, 0
	v_and_b32_e32 v17, 0xffff0000, v57
	v_lshlrev_b32_e32 v20, 16, v55
	v_and_b32_e32 v21, 0xffff0000, v55
	v_lshlrev_b32_e32 v14, 16, v56
	v_and_b32_e32 v15, 0xffff0000, v56
	v_lshlrev_b32_e32 v18, 16, v54
	v_and_b32_e32 v19, 0xffff0000, v54
	v_pk_add_f32 v[16:17], v[20:21], v[16:17]
	v_lshlrev_b32_e32 v20, 16, v53
	v_and_b32_e32 v21, 0xffff0000, v53
	v_pk_add_f32 v[14:15], v[18:19], v[14:15]
	v_lshlrev_b32_e32 v18, 16, v52
	v_and_b32_e32 v19, 0xffff0000, v52
	v_pk_fma_f32 v[16:17], v[16:17], 0.5, v[20:21] op_sel_hi:[1,0,1] neg_lo:[0,0,1] neg_hi:[0,0,1]
	v_pk_fma_f32 v[14:15], v[14:15], 0.5, v[18:19] op_sel_hi:[1,0,1] neg_lo:[0,0,1] neg_hi:[0,0,1]
	v_lshl_add_u32 v27, v9, 8, v25
	v_pk_fma_f32 v[10:11], v[14:15], v[210:211], v[18:19]
	v_pk_fma_f32 v[12:13], v[16:17], v[212:213], v[20:21]
	ds_write_b128 v27, v[10:13]
	v_lshlrev_b32_e32 v16, 16, v61
	v_and_b32_e32 v17, 0xffff0000, v61
	v_lshlrev_b32_e32 v20, 16, v63
	v_and_b32_e32 v21, 0xffff0000, v63
	v_lshlrev_b32_e32 v14, 16, v60
	v_and_b32_e32 v15, 0xffff0000, v60
	v_lshlrev_b32_e32 v18, 16, v62
	v_and_b32_e32 v19, 0xffff0000, v62
	v_pk_add_f32 v[16:17], v[20:21], v[16:17]
	v_lshlrev_b32_e32 v20, 16, v59
	v_and_b32_e32 v21, 0xffff0000, v59
	v_pk_add_f32 v[14:15], v[18:19], v[14:15]
	v_lshlrev_b32_e32 v18, 16, v58
	v_and_b32_e32 v19, 0xffff0000, v58
	v_pk_fma_f32 v[16:17], v[16:17], 0.5, v[20:21] op_sel_hi:[1,0,1] neg_lo:[0,0,1] neg_hi:[0,0,1]
	v_pk_fma_f32 v[14:15], v[14:15], 0.5, v[18:19] op_sel_hi:[1,0,1] neg_lo:[0,0,1] neg_hi:[0,0,1]
	v_pk_fma_f32 v[12:13], v[16:17], v[216:217], v[20:21]
	v_pk_fma_f32 v[10:11], v[14:15], v[214:215], v[18:19]
	ds_write_b128 v27, v[10:13] offset:8192
	v_lshlrev_b32_e32 v16, 16, v67
	v_and_b32_e32 v17, 0xffff0000, v67
	v_lshlrev_b32_e32 v20, 16, v69
	v_and_b32_e32 v21, 0xffff0000, v69
	v_lshlrev_b32_e32 v14, 16, v66
	v_and_b32_e32 v15, 0xffff0000, v66
	v_lshlrev_b32_e32 v18, 16, v68
	v_and_b32_e32 v19, 0xffff0000, v68
	v_pk_add_f32 v[16:17], v[20:21], v[16:17]
	v_lshlrev_b32_e32 v20, 16, v65
	v_and_b32_e32 v21, 0xffff0000, v65
	v_pk_add_f32 v[14:15], v[18:19], v[14:15]
	v_lshlrev_b32_e32 v18, 16, v64
	v_and_b32_e32 v19, 0xffff0000, v64
	v_pk_fma_f32 v[16:17], v[16:17], 0.5, v[20:21] op_sel_hi:[1,0,1] neg_lo:[0,0,1] neg_hi:[0,0,1]
	v_pk_fma_f32 v[14:15], v[14:15], 0.5, v[18:19] op_sel_hi:[1,0,1] neg_lo:[0,0,1] neg_hi:[0,0,1]
	v_pk_fma_f32 v[12:13], v[16:17], v[220:221], v[20:21]
	v_pk_fma_f32 v[10:11], v[14:15], v[218:219], v[18:19]
	ds_write_b128 v27, v[10:13] offset:16384
	v_lshlrev_b32_e32 v14, 16, v72
	v_and_b32_e32 v15, 0xffff0000, v72
	v_lshlrev_b32_e32 v18, 16, v74
	v_and_b32_e32 v19, 0xffff0000, v74
	v_pk_add_f32 v[14:15], v[18:19], v[14:15]
	v_lshlrev_b32_e32 v18, 16, v70
	v_and_b32_e32 v19, 0xffff0000, v70
	v_pk_fma_f32 v[14:15], v[14:15], 0.5, v[18:19] op_sel_hi:[1,0,1] neg_lo:[0,0,1] neg_hi:[0,0,1]
	v_lshlrev_b32_e32 v16, 16, v73
	v_pk_fma_f32 v[10:11], v[14:15], v[222:223], v[18:19]
	v_and_b32_e32 v17, 0xffff0000, v73
	v_lshlrev_b32_e32 v20, 16, v75
	v_and_b32_e32 v21, 0xffff0000, v75
	v_add_f32_e32 v10, v10, v10
	v_pk_add_f32 v[16:17], v[20:21], v[16:17]
	v_lshlrev_b32_e32 v20, 16, v71
	v_and_b32_e32 v21, 0xffff0000, v71
	v_mul_f32_e32 v10, 0x3fb8aa3b, v10
	v_exp_f32_e32 v14, v10
	v_add_f32_e32 v10, v11, v11
	v_pk_fma_f32 v[16:17], v[16:17], 0.5, v[20:21] op_sel_hi:[1,0,1] neg_lo:[0,0,1] neg_hi:[0,0,1]
	v_mul_f32_e32 v10, 0x3fb8aa3b, v10
	v_exp_f32_e32 v15, v10
	v_pk_fma_f32 v[10:11], v[16:17], v[224:225], v[20:21]
	v_add_f32_e32 v12, 1.0, v14
	v_add_f32_e32 v10, v10, v10
	v_add_f32_e32 v11, v11, v11
	v_mul_f32_e32 v10, 0x3fb8aa3b, v10
	v_mul_f32_e32 v11, 0x3fb8aa3b, v11
	v_exp_f32_e32 v10, v10
	v_exp_f32_e32 v11, v11
	v_add_f32_e32 v13, 1.0, v15
	v_rcp_f32_e32 v12, v12
	v_add_f32_e32 v10, 1.0, v10
	v_add_f32_e32 v11, 1.0, v11
	v_rcp_f32_e32 v13, v13
	v_rcp_f32_e32 v10, v10
	v_rcp_f32_e32 v11, v11
	v_lshlrev_b32_e32 v24, 3, v8
	v_mul_lo_u32 v26, v9, s76
	v_pk_fma_f32 v[12:13], v[12:13], 2.0, 1.0 op_sel_hi:[1,0,0] neg_lo:[1,0,0] neg_hi:[1,0,0]
	v_pk_fma_f32 v[10:11], v[10:11], 2.0, 1.0 op_sel_hi:[1,0,0] neg_lo:[1,0,0] neg_hi:[1,0,0]
	v_add3_u32 v14, s74, v24, v26
	v_cvt_pk_bf16_f32 v12, v12, v13
	v_cvt_pk_bf16_f32 v13, v10, v11
	ds_write_b64 v14, v[12:13]
	v_lshlrev_b32_e32 v14, 16, v78
	v_and_b32_e32 v15, 0xffff0000, v78
	v_lshlrev_b32_e32 v18, 16, v80
	v_and_b32_e32 v19, 0xffff0000, v80
	v_lshlrev_b32_e32 v16, 16, v79
	v_and_b32_e32 v17, 0xffff0000, v79
	v_lshlrev_b32_e32 v20, 16, v81
	v_and_b32_e32 v21, 0xffff0000, v81
	v_pk_add_f32 v[14:15], v[18:19], v[14:15]
	v_lshlrev_b32_e32 v18, 16, v76
	v_and_b32_e32 v19, 0xffff0000, v76
	v_pk_add_f32 v[16:17], v[20:21], v[16:17]
	v_lshlrev_b32_e32 v20, 16, v77
	v_and_b32_e32 v21, 0xffff0000, v77
	v_pk_fma_f32 v[14:15], v[14:15], 0.5, v[18:19] op_sel_hi:[1,0,1] neg_lo:[0,0,1] neg_hi:[0,0,1]
	v_pk_fma_f32 v[16:17], v[16:17], 0.5, v[20:21] op_sel_hi:[1,0,1] neg_lo:[0,0,1] neg_hi:[0,0,1]
	v_pk_fma_f32 v[10:11], v[14:15], v[226:227], v[18:19]
	v_pk_fma_f32 v[12:13], v[16:17], v[228:229], v[20:21]
	v_cvt_pk_bf16_f32 v10, v10, v11
	v_cvt_pk_bf16_f32 v11, v12, v13
	v_cndmask_b32_e64 v12, 0, 1, s[36:37]
	v_add3_u32 v24, s75, v24, v26
	v_cmp_ne_u32_e64 s[12:13], 1, v12
	s_andn2_b64 vcc, exec, s[36:37]
	ds_write_b64 v24, v[10:11]
	s_cbranch_vccnz .LBB0_491
	v_lshlrev_b32_e32 v12, 16, v51
	v_lshlrev_b32_e32 v13, 16, v49
	v_lshlrev_b32_e32 v10, 16, v47
	v_add_f32_e32 v12, v12, v13
	v_fma_f32 v12, v12, 0.5, -v10
	v_fmac_f32_e32 v10, v12, v230
	v_mul_f32_e32 v10, 0xbfb8aa3b, v10
	v_exp_f32_e32 v12, v10
	v_add_u32_e32 v10, s46, v9
	v_ashrrev_i32_e32 v11, 31, v10
	v_lshl_add_u64 v[10:11], s[40:41], 0, v[10:11]
	v_add_f32_e32 v9, 1.0, v12
	v_rcp_f32_e32 v9, v9
	v_lshlrev_b64 v[10:11], 8, v[10:11]
	v_lshl_add_u64 v[10:11], s[42:43], 0, v[10:11]
	v_lshlrev_b32_e32 v8, 1, v8
	v_cvt_pk_bf16_f32 v12, v9, s0
	v_mov_b32_e32 v9, v38
	v_lshl_add_u64 v[8:9], v[10:11], 0, v[8:9]
	global_store_short v[8:9], v12, off
